# final rmsnorm phase: non-temporal hint on the 16 stores of the never-re-read f32 output
# speedup vs baseline: 1.0008x; 1.0008x over previous
.LBB0_848:
	global_load_dword v36, v17, s[2:3]
	global_load_dwordx4 v[40:43], v[18:19], off offset:16
	global_load_dwordx4 v[44:47], v[18:19], off
	s_mul_hi_i32 s0, s8, 0x81020409
	s_add_i32 s0, s0, s8
	s_lshr_b32 s1, s0, 31
	s_ashr_i32 s0, s0, 7
	s_add_i32 s0, s0, s1
	s_lshl_b32 s1, s0, 1
	s_lshl_b32 s0, s0, 6
	s_add_i32 s1, s8, s1
	s_add_i32 s0, s9, s0
	s_add_i32 s1, s1, 2
	s_and_b32 s24, s0, 0x1e0
	s_ashr_i32 s0, s1, 4
	s_ashr_i32 s1, s0, 31
	s_lshl_b64 s[0:1], s[0:1], 17
	s_add_u32 s0, s22, s0
	s_addc_u32 s1, s23, s1
	s_lshl_b32 s24, s24, 1
	s_add_u32 s0, s0, s24
	s_addc_u32 s1, s1, 0
	v_lshl_add_u64 v[0:1], s[0:1], 0, v[16:17]
	v_lshl_add_u64 v[0:1], v[0:1], 0, v[34:35]
	global_load_dwordx4 v[48:51], v[0:1], off
	v_add_co_u32_e32 v64, vcc, s19, v32
	s_add_i32 s8, s8, s18
	s_nop 0
	v_addc_co_u32_e32 v65, vcc, -1, v33, vcc
	v_add_co_u32_e32 v2, vcc, s12, v0
	s_add_u32 s2, s2, s4
	s_nop 0
	v_addc_co_u32_e32 v3, vcc, 0, v1, vcc
	v_add_co_u32_e32 v4, vcc, s13, v0
	s_addc_u32 s3, s3, s5
	s_nop 0
	v_addc_co_u32_e32 v5, vcc, 0, v1, vcc
	v_add_co_u32_e32 v6, vcc, s14, v0
	s_add_i32 s9, s9, s10
	s_nop 0
	v_addc_co_u32_e32 v7, vcc, 0, v1, vcc
	v_add_co_u32_e32 v66, vcc, s15, v0
	global_load_dwordx4 v[52:55], v[2:3], off
	global_load_dwordx4 v[56:59], v[4:5], off
	global_load_dwordx4 v[60:63], v[6:7], off
	v_addc_co_u32_e32 v67, vcc, 0, v1, vcc
	v_add_co_u32_e32 v2, vcc, s16, v0
	s_cmpk_gt_i32 s8, 0x3fff
	s_nop 0
	v_addc_co_u32_e32 v3, vcc, 0, v1, vcc
	v_add_co_u32_e32 v68, vcc, s17, v0
	global_load_dwordx4 v[12:15], v[66:67], off
	global_load_dwordx4 v[8:11], v[2:3], off
	v_addc_co_u32_e32 v69, vcc, 0, v1, vcc
	v_add_co_u32_e32 v66, vcc, 0x1c000, v0
	s_waitcnt vmcnt(8)
	v_fmamk_f32 v36, v36, 0x39800000, v37
	v_addc_co_u32_e32 v67, vcc, 0, v1, vcc
	v_mul_f32_e32 v39, 0x4f800000, v36
	v_cmp_gt_f32_e32 vcc, s11, v36
	global_load_dwordx4 v[4:7], v[68:69], off
	global_load_dwordx4 v[0:3], v[66:67], off
	v_cndmask_b32_e32 v36, v36, v39, vcc
	v_sqrt_f32_e32 v39, v36
	s_nop 0
	v_add_u32_e32 v66, -1, v39
	v_add_u32_e32 v67, 1, v39
	v_fma_f32 v68, -v66, v39, v36
	v_fma_f32 v69, -v67, v39, v36
	v_cmp_ge_f32_e64 s[0:1], 0, v68
	s_waitcnt vmcnt(7)
	v_lshlrev_b32_e32 v68, 16, v50
	v_cndmask_b32_e64 v39, v39, v66, s[0:1]
	v_cmp_lt_f32_e64 s[0:1], 0, v69
	v_and_b32_e32 v69, 0xffff0000, v50
	v_lshlrev_b32_e32 v50, 16, v51
	v_cndmask_b32_e64 v39, v39, v67, s[0:1]
	v_mul_f32_e32 v66, 0x37800000, v39
	v_cndmask_b32_e32 v39, v39, v66, vcc
	v_cmp_class_f32_e32 vcc, v36, v38
	v_lshlrev_b32_e32 v66, 16, v48
	v_and_b32_e32 v67, 0xffff0000, v48
	v_cndmask_b32_e32 v36, v39, v36, vcc
	v_div_scale_f32 v39, s[0:1], v36, v36, 1.0
	v_rcp_f32_e32 v71, v39
	v_div_scale_f32 v70, vcc, 1.0, v36, 1.0
	v_lshlrev_b32_e32 v48, 16, v49
	v_fma_f32 v72, -v39, v71, 1.0
	v_fmac_f32_e32 v71, v72, v71
	v_mul_f32_e32 v72, v70, v71
	v_fma_f32 v73, -v39, v72, v70
	v_fmac_f32_e32 v72, v73, v71
	v_fma_f32 v39, -v39, v72, v70
	v_div_fmas_f32 v39, v39, v71, v72
	v_and_b32_e32 v49, 0xffff0000, v49
	v_div_fixup_f32 v36, v39, v36, 1.0
	v_and_b32_e32 v51, 0xffff0000, v51
	v_pk_mul_f32 v[66:67], v[36:37], v[66:67] op_sel_hi:[0,1]
	v_pk_mul_f32 v[48:49], v[36:37], v[48:49] op_sel_hi:[0,1]
	v_pk_mul_f32 v[68:69], v[36:37], v[68:69] op_sel_hi:[0,1]
	v_pk_mul_f32 v[50:51], v[36:37], v[50:51] op_sel_hi:[0,1]
	v_pk_mul_f32 v[46:47], v[46:47], v[48:49]
	v_pk_mul_f32 v[44:45], v[44:45], v[66:67]
	v_pk_mul_f32 v[42:43], v[42:43], v[50:51]
	v_pk_mul_f32 v[40:41], v[40:41], v[68:69]
	global_store_dwordx4 v[64:65], v[44:47], off offset:-2064 nt
	global_store_dwordx4 v[64:65], v[40:43], off offset:-2048 nt
	global_load_dwordx4 v[40:43], v[18:19], off offset:2048
	s_nop 0
	global_load_dwordx4 v[44:47], v[18:19], off offset:2064
	s_waitcnt vmcnt(10)
	v_lshlrev_b32_e32 v50, 16, v52
	v_and_b32_e32 v51, 0xffff0000, v52
	v_lshlrev_b32_e32 v52, 16, v53
	v_and_b32_e32 v53, 0xffff0000, v53
	v_lshlrev_b32_e32 v66, 16, v54
	v_and_b32_e32 v67, 0xffff0000, v54
	v_lshlrev_b32_e32 v54, 16, v55
	v_and_b32_e32 v55, 0xffff0000, v55
	v_pk_mul_f32 v[52:53], v[36:37], v[52:53] op_sel_hi:[0,1]
	v_pk_mul_f32 v[50:51], v[36:37], v[50:51] op_sel_hi:[0,1]
	v_add_co_u32_e32 v48, vcc, s20, v32
	v_pk_mul_f32 v[54:55], v[36:37], v[54:55] op_sel_hi:[0,1]
	v_pk_mul_f32 v[66:67], v[36:37], v[66:67] op_sel_hi:[0,1]
	v_addc_co_u32_e32 v49, vcc, -1, v33, vcc
	s_waitcnt vmcnt(1)
	v_pk_mul_f32 v[40:41], v[40:41], v[50:51]
	v_pk_mul_f32 v[42:43], v[42:43], v[52:53]
	s_waitcnt vmcnt(0)
	v_pk_mul_f32 v[44:45], v[44:45], v[66:67]
	v_pk_mul_f32 v[46:47], v[46:47], v[54:55]
	global_store_dwordx4 v[64:65], v[40:43], off offset:-16 nt
	global_store_dwordx4 v[48:49], v[44:47], off offset:-4096 nt
	global_load_dwordx4 v[40:43], v[20:21], off
	s_nop 0
	global_load_dwordx4 v[44:47], v[20:21], off offset:16
	v_lshlrev_b32_e32 v50, 16, v56
	v_and_b32_e32 v51, 0xffff0000, v56
	v_lshlrev_b32_e32 v52, 16, v57
	v_and_b32_e32 v53, 0xffff0000, v57
	v_lshlrev_b32_e32 v54, 16, v58
	v_and_b32_e32 v55, 0xffff0000, v58
	v_lshlrev_b32_e32 v56, 16, v59
	v_and_b32_e32 v57, 0xffff0000, v59
	v_pk_mul_f32 v[52:53], v[36:37], v[52:53] op_sel_hi:[0,1]
	v_pk_mul_f32 v[50:51], v[36:37], v[50:51] op_sel_hi:[0,1]
	v_pk_mul_f32 v[56:57], v[36:37], v[56:57] op_sel_hi:[0,1]
	v_pk_mul_f32 v[54:55], v[36:37], v[54:55] op_sel_hi:[0,1]
	s_waitcnt vmcnt(1)
	v_pk_mul_f32 v[40:41], v[40:41], v[50:51]
	v_pk_mul_f32 v[42:43], v[42:43], v[52:53]
	s_waitcnt vmcnt(0)
	v_pk_mul_f32 v[44:45], v[44:45], v[54:55]
	v_pk_mul_f32 v[46:47], v[46:47], v[56:57]
	global_store_dwordx4 v[48:49], v[40:43], off offset:-2064 nt
	global_store_dwordx4 v[48:49], v[44:47], off offset:-2048 nt
	global_load_dwordx4 v[40:43], v[22:23], off
	s_nop 0
	global_load_dwordx4 v[44:47], v[22:23], off offset:16
	v_lshlrev_b32_e32 v50, 16, v60
	v_and_b32_e32 v51, 0xffff0000, v60
	v_lshlrev_b32_e32 v52, 16, v61
	v_and_b32_e32 v53, 0xffff0000, v61
	v_lshlrev_b32_e32 v54, 16, v62
	v_and_b32_e32 v55, 0xffff0000, v62
	v_lshlrev_b32_e32 v56, 16, v63
	v_and_b32_e32 v57, 0xffff0000, v63
	v_pk_mul_f32 v[52:53], v[36:37], v[52:53] op_sel_hi:[0,1]
	v_pk_mul_f32 v[50:51], v[36:37], v[50:51] op_sel_hi:[0,1]
	v_pk_mul_f32 v[56:57], v[36:37], v[56:57] op_sel_hi:[0,1]
	v_pk_mul_f32 v[54:55], v[36:37], v[54:55] op_sel_hi:[0,1]
	s_waitcnt vmcnt(1)
	v_pk_mul_f32 v[40:41], v[40:41], v[50:51]
	v_pk_mul_f32 v[42:43], v[42:43], v[52:53]
	s_waitcnt vmcnt(0)
	v_pk_mul_f32 v[44:45], v[44:45], v[54:55]
	v_pk_mul_f32 v[46:47], v[46:47], v[56:57]
	global_store_dwordx4 v[48:49], v[40:43], off offset:-16 nt
	global_store_dwordx4 v[48:49], v[44:47], off nt
	global_load_dwordx4 v[40:43], v[24:25], off
	s_nop 0
	global_load_dwordx4 v[44:47], v[24:25], off offset:16
	v_lshlrev_b32_e32 v50, 16, v12
	v_and_b32_e32 v51, 0xffff0000, v12
	v_lshlrev_b32_e32 v12, 16, v13
	v_and_b32_e32 v13, 0xffff0000, v13
	v_add_co_u32_e32 v48, vcc, s21, v32
	v_lshlrev_b32_e32 v52, 16, v14
	v_and_b32_e32 v53, 0xffff0000, v14
	v_lshlrev_b32_e32 v14, 16, v15
	v_and_b32_e32 v15, 0xffff0000, v15
	v_pk_mul_f32 v[54:55], v[36:37], v[12:13] op_sel_hi:[0,1]
	v_pk_mul_f32 v[12:13], v[36:37], v[50:51] op_sel_hi:[0,1]
	v_addc_co_u32_e32 v49, vcc, -1, v33, vcc
	v_pk_mul_f32 v[50:51], v[36:37], v[14:15] op_sel_hi:[0,1]
	v_pk_mul_f32 v[52:53], v[36:37], v[52:53] op_sel_hi:[0,1]
	s_waitcnt vmcnt(1)
	v_pk_mul_f32 v[12:13], v[40:41], v[12:13]
	v_pk_mul_f32 v[14:15], v[42:43], v[54:55]
	s_waitcnt vmcnt(0)
	v_pk_mul_f32 v[40:41], v[44:45], v[52:53]
	v_pk_mul_f32 v[42:43], v[46:47], v[50:51]
	global_store_dwordx4 v[48:49], v[12:15], off offset:-2064 nt
	global_store_dwordx4 v[48:49], v[40:43], off offset:-2048 nt
	global_load_dwordx4 v[12:15], v[26:27], off
	s_nop 0
	global_load_dwordx4 v[40:43], v[26:27], off offset:16
	v_lshlrev_b32_e32 v44, 16, v8
	v_and_b32_e32 v45, 0xffff0000, v8
	v_lshlrev_b32_e32 v8, 16, v9
	v_and_b32_e32 v9, 0xffff0000, v9
	v_lshlrev_b32_e32 v46, 16, v10
	v_and_b32_e32 v47, 0xffff0000, v10
	v_lshlrev_b32_e32 v10, 16, v11
	v_and_b32_e32 v11, 0xffff0000, v11
	v_pk_mul_f32 v[50:51], v[36:37], v[8:9] op_sel_hi:[0,1]
	v_pk_mul_f32 v[8:9], v[36:37], v[44:45] op_sel_hi:[0,1]
	v_pk_mul_f32 v[44:45], v[36:37], v[10:11] op_sel_hi:[0,1]
	v_pk_mul_f32 v[46:47], v[36:37], v[46:47] op_sel_hi:[0,1]
	s_waitcnt vmcnt(1)
	v_pk_mul_f32 v[8:9], v[12:13], v[8:9]
	v_pk_mul_f32 v[10:11], v[14:15], v[50:51]
	s_waitcnt vmcnt(0)
	v_pk_mul_f32 v[12:13], v[40:41], v[46:47]
	v_pk_mul_f32 v[14:15], v[42:43], v[44:45]
	global_store_dwordx4 v[48:49], v[8:11], off offset:-16 nt
	global_store_dwordx4 v[32:33], v[12:15], off offset:-4096 nt
	global_load_dwordx4 v[8:11], v[28:29], off
	s_nop 0
	global_load_dwordx4 v[12:15], v[28:29], off offset:16
	v_lshlrev_b32_e32 v40, 16, v4
	v_and_b32_e32 v41, 0xffff0000, v4
	v_lshlrev_b32_e32 v4, 16, v5
	v_and_b32_e32 v5, 0xffff0000, v5
	v_lshlrev_b32_e32 v42, 16, v6
	v_and_b32_e32 v43, 0xffff0000, v6
	v_lshlrev_b32_e32 v6, 16, v7
	v_and_b32_e32 v7, 0xffff0000, v7
	v_pk_mul_f32 v[44:45], v[36:37], v[4:5] op_sel_hi:[0,1]
	v_pk_mul_f32 v[4:5], v[36:37], v[40:41] op_sel_hi:[0,1]
	v_pk_mul_f32 v[40:41], v[36:37], v[6:7] op_sel_hi:[0,1]
	v_pk_mul_f32 v[42:43], v[36:37], v[42:43] op_sel_hi:[0,1]
	s_waitcnt vmcnt(1)
	v_pk_mul_f32 v[4:5], v[8:9], v[4:5]
	v_pk_mul_f32 v[6:7], v[10:11], v[44:45]
	s_waitcnt vmcnt(0)
	v_pk_mul_f32 v[8:9], v[12:13], v[42:43]
	v_pk_mul_f32 v[10:11], v[14:15], v[40:41]
	global_store_dwordx4 v[32:33], v[4:7], off offset:-2064 nt
	global_store_dwordx4 v[32:33], v[8:11], off offset:-2048 nt
	global_load_dwordx4 v[4:7], v[30:31], off
	s_nop 0
	global_load_dwordx4 v[8:11], v[30:31], off offset:16
	v_lshlrev_b32_e32 v12, 16, v0
	v_and_b32_e32 v13, 0xffff0000, v0
	v_lshlrev_b32_e32 v0, 16, v1
	v_and_b32_e32 v1, 0xffff0000, v1
	v_lshlrev_b32_e32 v14, 16, v2
	v_and_b32_e32 v15, 0xffff0000, v2
	v_lshlrev_b32_e32 v2, 16, v3
	v_and_b32_e32 v3, 0xffff0000, v3
	v_pk_mul_f32 v[40:41], v[36:37], v[0:1] op_sel_hi:[0,1]
	v_pk_mul_f32 v[0:1], v[36:37], v[12:13] op_sel_hi:[0,1]
	v_pk_mul_f32 v[12:13], v[36:37], v[2:3] op_sel_hi:[0,1]
	v_pk_mul_f32 v[14:15], v[36:37], v[14:15] op_sel_hi:[0,1]
	s_waitcnt vmcnt(1)
	v_pk_mul_f32 v[0:1], v[4:5], v[0:1]
	v_pk_mul_f32 v[2:3], v[6:7], v[40:41]
	s_waitcnt vmcnt(0)
	v_pk_mul_f32 v[4:5], v[8:9], v[14:15]
	v_pk_mul_f32 v[6:7], v[10:11], v[12:13]
	global_store_dwordx4 v[32:33], v[0:3], off offset:-16 nt
	global_store_dwordx4 v[32:33], v[4:7], off nt
	v_lshl_add_u64 v[32:33], v[32:33], 0, s[6:7]
	s_cbranch_scc0 .LBB0_848
